# band-attention tile loads reordered so the four 32-byte pieces of each 128-byte K/V row segment are requested by consecutive instructions (two counted waits re-derived)
# speedup vs baseline: 1.0604x; 1.0029x over previous
.LBB0_804:
	v_lshl_add_u64 v[60:61], v[198:199], 0, v[186:187]
	v_add_co_u32_e32 v62, vcc, s27, v60
	s_cmp_eq_u32 s14, s43
	s_nop 0
	v_addc_co_u32_e32 v63, vcc, 0, v61, vcc
	v_add_co_u32_e32 v60, vcc, 0x11f03000, v60
	s_nop 1
	v_addc_co_u32_e32 v61, vcc, 0, v61, vcc
	global_load_dwordx4 v[168:171], v[62:63], off offset:2048
	global_load_dwordx4 v[160:163], v[62:63], off offset:2080
	global_load_dwordx4 v[152:155], v[62:63], off offset:2112
	global_load_dwordx4 v[144:147], v[62:63], off offset:2144
	global_load_dwordx4 v[172:175], v[60:61], off offset:1024
	global_load_dwordx4 v[164:167], v[60:61], off offset:1056
	global_load_dwordx4 v[156:159], v[60:61], off offset:1088
	global_load_dwordx4 v[148:151], v[60:61], off offset:1120
	s_cbranch_scc1 .LBB0_806
	v_lshl_add_u64 v[60:61], v[200:201], 0, v[186:187]
	v_add_co_u32_e32 v62, vcc, 0x11fb0000, v60
	s_nop 1
	v_addc_co_u32_e32 v63, vcc, 0, v61, vcc
	v_add_co_u32_e32 v60, vcc, 0x12008000, v60
	s_nop 1
	v_addc_co_u32_e32 v61, vcc, 0, v61, vcc
	global_load_dwordx4 v[136:139], v[62:63], off offset:1024
	global_load_dwordx4 v[132:135], v[62:63], off offset:1056
	global_load_dwordx4 v[120:123], v[62:63], off offset:1088
	global_load_dwordx4 v[116:119], v[62:63], off offset:1120
	global_load_dwordx4 v[140:143], v[60:61], off offset:1024
	global_load_dwordx4 v[128:131], v[60:61], off offset:1056
	global_load_dwordx4 v[124:127], v[60:61], off offset:1088
	global_load_dwordx4 v[112:115], v[60:61], off offset:1120

.LBB0_810:
	s_nop 8
	v_max_f32_e32 v64, v48, v48
	v_max_f32_e32 v65, v32, v32
	v_max_f32_e32 v64, v65, v64
	v_max3_f32 v64, v64, v33, v49
	v_max3_f32 v64, v64, v34, v50
	v_max3_f32 v64, v64, v35, v51
	v_max3_f32 v64, v64, v36, v52
	v_max3_f32 v64, v64, v37, v53
	v_max3_f32 v64, v64, v38, v54
	v_max3_f32 v64, v64, v39, v55
	v_max3_f32 v64, v64, v40, v56
	v_max3_f32 v64, v64, v41, v57
	v_max3_f32 v64, v64, v42, v58
	v_max3_f32 v64, v64, v43, v59
	v_max3_f32 v64, v64, v44, v60
	v_max3_f32 v64, v64, v45, v61
	v_max3_f32 v64, v64, v46, v62
	v_max3_f32 v64, v64, v47, v63
	ds_bpermute_b32 v65, v191, v64
	s_waitcnt vmcnt(7)
	v_lshrrev_b32_e32 v72, 16, v168
	s_waitcnt vmcnt(3)
	v_and_or_b32 v72, v172, s31, v72
	v_add_u32_e32 v93, v203, v204
	s_add_i32 s43, s43, 64
	s_waitcnt lgkmcnt(0)
	v_max3_f32 v195, v234, v64, v65
	v_sub_f32_e32 v32, v32, v195
	v_cmp_gt_f32_e32 vcc, s30, v32
	v_sub_f32_e32 v48, v48, v195
	v_cmp_gt_f32_e64 s[12:13], s30, v48
	v_cndmask_b32_e32 v64, 0, v230, vcc
	v_add_f32_e32 v32, v32, v64
	v_exp_f32_e32 v32, v32
	v_sub_f32_e32 v33, v33, v195
	v_cndmask_b32_e64 v64, 0, v230, s[12:13]
	v_cndmask_b32_e32 v65, 0, v231, vcc
	v_cmp_gt_f32_e32 vcc, s30, v33
	v_ldexp_f32 v68, v32, v65
	v_add_f32_e32 v32, v48, v64
	v_cndmask_b32_e32 v48, 0, v230, vcc
	v_exp_f32_e32 v32, v32
	v_add_f32_e32 v33, v33, v48
	v_exp_f32_e32 v33, v33
	v_cndmask_b32_e64 v48, 0, v231, s[12:13]
	v_ldexp_f32 v70, v32, v48
	v_cndmask_b32_e32 v32, 0, v231, vcc
	v_ldexp_f32 v76, v33, v32
	v_sub_f32_e32 v32, v49, v195
	v_cmp_gt_f32_e32 vcc, s30, v32
	v_sub_f32_e32 v34, v34, v195
	v_sub_f32_e32 v41, v41, v195
	v_cndmask_b32_e32 v33, 0, v230, vcc
	v_add_f32_e32 v32, v32, v33
	v_cndmask_b32_e32 v33, 0, v231, vcc
	v_cmp_gt_f32_e32 vcc, s30, v34
	v_exp_f32_e32 v32, v32
	v_sub_f32_e32 v42, v42, v195
	v_cndmask_b32_e32 v48, 0, v230, vcc
	v_add_f32_e32 v34, v34, v48
	v_exp_f32_e32 v34, v34
	v_ldexp_f32 v88, v32, v33
	v_cndmask_b32_e32 v32, 0, v231, vcc
	v_sub_f32_e32 v43, v43, v195
	v_ldexp_f32 v77, v34, v32
	v_sub_f32_e32 v32, v50, v195
	v_cmp_gt_f32_e32 vcc, s30, v32
	v_sub_f32_e32 v34, v35, v195
	v_sub_f32_e32 v44, v44, v195
	v_cndmask_b32_e32 v33, 0, v230, vcc
	v_add_f32_e32 v32, v32, v33
	v_cndmask_b32_e32 v33, 0, v231, vcc
	v_cmp_gt_f32_e32 vcc, s30, v34
	v_exp_f32_e32 v32, v32
	v_sub_f32_e32 v45, v45, v195
	v_cndmask_b32_e32 v35, 0, v230, vcc
	v_add_f32_e32 v34, v34, v35
	v_exp_f32_e32 v34, v34
	v_ldexp_f32 v89, v32, v33
	v_cndmask_b32_e32 v32, 0, v231, vcc
	v_sub_f32_e32 v46, v46, v195
	v_ldexp_f32 v78, v34, v32
	v_sub_f32_e32 v32, v51, v195
	v_cmp_gt_f32_e32 vcc, s30, v32
	v_sub_f32_e32 v34, v36, v195
	v_sub_f32_e32 v71, v234, v195
	v_cndmask_b32_e32 v33, 0, v230, vcc
	v_add_f32_e32 v32, v32, v33
	v_cndmask_b32_e32 v33, 0, v231, vcc
	v_cmp_gt_f32_e32 vcc, s30, v34
	v_exp_f32_e32 v32, v32
	v_add_f32_e32 v69, v76, v88
	v_cndmask_b32_e32 v35, 0, v230, vcc
	v_add_f32_e32 v34, v34, v35
	v_exp_f32_e32 v34, v34
	v_ldexp_f32 v91, v32, v33
	v_cndmask_b32_e32 v32, 0, v231, vcc
	v_add_f32_e32 v90, v77, v89
	v_ldexp_f32 v49, v34, v32
	v_sub_f32_e32 v32, v52, v195
	v_cmp_gt_f32_e32 vcc, s30, v32
	v_add_f32_e32 v92, v78, v91
	v_cvt_pk_bf16_f32 v76, v68, v76
	v_cvt_pk_bf16_f32 v77, v77, v78
	s_add_i32 s40, s40, 1
	v_cndmask_b32_e32 v33, 0, v230, vcc
	v_add_f32_e32 v32, v32, v33
	v_sub_f32_e32 v33, v37, v195
	v_cmp_gt_f32_e64 s[12:13], s30, v33
	v_exp_f32_e32 v32, v32
	v_subrev_u32_e32 v232, 64, v232
	v_cndmask_b32_e64 v34, 0, v230, s[12:13]
	v_add_f32_e32 v33, v33, v34
	v_exp_f32_e32 v33, v33
	v_cndmask_b32_e32 v34, 0, v231, vcc
	v_ldexp_f32 v35, v32, v34
	v_cndmask_b32_e64 v32, 0, v231, s[12:13]
	v_ldexp_f32 v48, v33, v32
	v_sub_f32_e32 v32, v53, v195
	v_cmp_gt_f32_e32 vcc, s30, v32
	v_sub_f32_e32 v34, v38, v195
	v_cvt_pk_bf16_f32 v78, v49, v48
	v_lshl_add_u64 v[198:199], v[198:199], 0, s[18:19]
	v_cndmask_b32_e32 v33, 0, v230, vcc
	v_add_f32_e32 v32, v32, v33
	v_cndmask_b32_e32 v33, 0, v231, vcc
	v_cmp_gt_f32_e32 vcc, s30, v34
	v_exp_f32_e32 v32, v32
	s_cmp_eq_u32 s14, s43
	v_cndmask_b32_e32 v36, 0, v230, vcc
	v_add_f32_e32 v34, v34, v36
	v_exp_f32_e32 v36, v34
	v_cndmask_b32_e32 v37, 0, v231, vcc
	v_ldexp_f32 v34, v32, v33
	v_pk_add_f32 v[32:33], v[48:49], v[34:35]
	v_ldexp_f32 v53, v36, v37
	v_sub_f32_e32 v36, v54, v195
	v_cmp_gt_f32_e32 vcc, s30, v36
	v_lshl_add_u64 v[200:201], v[200:201], 0, s[18:19]
	s_nop 0
	v_cndmask_b32_e32 v37, 0, v230, vcc
	v_add_f32_e32 v36, v36, v37
	v_sub_f32_e32 v37, v39, v195
	v_cmp_gt_f32_e64 s[12:13], s30, v37
	v_exp_f32_e32 v36, v36
	s_nop 0
	v_cndmask_b32_e64 v38, 0, v230, s[12:13]
	v_add_f32_e32 v37, v37, v38
	v_exp_f32_e32 v37, v37
	v_cndmask_b32_e32 v38, 0, v231, vcc
	v_ldexp_f32 v39, v36, v38
	v_cndmask_b32_e64 v36, 0, v231, s[12:13]
	v_ldexp_f32 v52, v37, v36
	v_sub_f32_e32 v36, v55, v195
	v_cmp_gt_f32_e32 vcc, s30, v36
	v_sub_f32_e32 v38, v40, v195
	v_cmp_gt_f32_e64 s[12:13], s30, v41
	v_cndmask_b32_e32 v37, 0, v230, vcc
	v_add_f32_e32 v36, v36, v37
	v_cndmask_b32_e32 v37, 0, v231, vcc
	v_cmp_gt_f32_e32 vcc, s30, v38
	v_cvt_pk_bf16_f32 v79, v53, v52
	v_exp_f32_e32 v36, v36
	s_nop 0
	v_cndmask_b32_e32 v40, 0, v230, vcc
	v_add_f32_e32 v38, v38, v40
	v_exp_f32_e32 v40, v38
	v_cndmask_b32_e32 v50, 0, v231, vcc
	v_ldexp_f32 v38, v36, v37
	v_pk_add_f32 v[36:37], v[52:53], v[38:39]
	v_ldexp_f32 v55, v40, v50
	v_sub_f32_e32 v40, v56, v195
	v_cmp_gt_f32_e32 vcc, s30, v40
	s_nop 1
	v_cndmask_b32_e32 v50, 0, v230, vcc
	v_add_f32_e32 v40, v40, v50
	v_cndmask_b32_e64 v50, 0, v230, s[12:13]
	v_exp_f32_e32 v40, v40
	v_add_f32_e32 v41, v41, v50
	v_exp_f32_e32 v50, v41
	v_cndmask_b32_e32 v41, 0, v231, vcc
	v_ldexp_f32 v41, v40, v41
	v_cndmask_b32_e64 v40, 0, v231, s[12:13]
	v_ldexp_f32 v54, v50, v40
	v_sub_f32_e32 v40, v57, v195
	v_cmp_gt_f32_e32 vcc, s30, v40
	v_cmp_gt_f32_e64 s[12:13], s30, v43
	v_cvt_pk_bf16_f32 v52, v55, v54
	s_nop 0
	v_cndmask_b32_e32 v50, 0, v230, vcc
	v_add_f32_e32 v40, v40, v50
	v_cndmask_b32_e32 v50, 0, v231, vcc
	v_cmp_gt_f32_e32 vcc, s30, v42
	v_exp_f32_e32 v40, v40
	s_nop 0
	v_cndmask_b32_e32 v51, 0, v230, vcc
	v_add_f32_e32 v42, v42, v51
	v_exp_f32_e32 v42, v42
	v_cndmask_b32_e32 v56, 0, v231, vcc
	v_ldexp_f32 v40, v40, v50
	v_pk_add_f32 v[50:51], v[54:55], v[40:41]
	v_ldexp_f32 v65, v42, v56
	v_sub_f32_e32 v42, v58, v195
	v_cmp_gt_f32_e32 vcc, s30, v42
	s_nop 1
	v_cndmask_b32_e32 v56, 0, v230, vcc
	v_add_f32_e32 v42, v42, v56
	v_cndmask_b32_e64 v56, 0, v230, s[12:13]
	v_exp_f32_e32 v42, v42
	v_add_f32_e32 v43, v43, v56
	v_exp_f32_e32 v56, v43
	v_cndmask_b32_e32 v43, 0, v231, vcc
	v_ldexp_f32 v43, v42, v43
	v_cndmask_b32_e64 v42, 0, v231, s[12:13]
	v_ldexp_f32 v64, v56, v42
	v_sub_f32_e32 v42, v59, v195
	v_cmp_gt_f32_e32 vcc, s30, v42
	v_cmp_gt_f32_e64 s[12:13], s30, v45
	v_cvt_pk_bf16_f32 v53, v65, v64
	s_nop 0
	v_cndmask_b32_e32 v56, 0, v230, vcc
	v_add_f32_e32 v42, v42, v56
	v_cndmask_b32_e32 v56, 0, v231, vcc
	v_cmp_gt_f32_e32 vcc, s30, v44
	v_exp_f32_e32 v42, v42
	s_nop 0
	v_cndmask_b32_e32 v57, 0, v230, vcc
	v_add_f32_e32 v44, v44, v57
	v_exp_f32_e32 v44, v44
	v_cndmask_b32_e32 v58, 0, v231, vcc
	v_ldexp_f32 v42, v42, v56
	v_pk_add_f32 v[56:57], v[64:65], v[42:43]
	v_ldexp_f32 v67, v44, v58
	v_sub_f32_e32 v44, v60, v195
	v_cmp_gt_f32_e32 vcc, s30, v44
	s_nop 1
	v_cndmask_b32_e32 v58, 0, v230, vcc
	v_add_f32_e32 v44, v44, v58
	v_cndmask_b32_e64 v58, 0, v230, s[12:13]
	v_exp_f32_e32 v44, v44
	v_add_f32_e32 v45, v45, v58
	v_exp_f32_e32 v58, v45
	v_cndmask_b32_e32 v45, 0, v231, vcc
	v_ldexp_f32 v45, v44, v45
	v_cndmask_b32_e64 v44, 0, v231, s[12:13]
	v_ldexp_f32 v66, v58, v44
	v_sub_f32_e32 v44, v61, v195
	v_cmp_gt_f32_e32 vcc, s30, v44
	v_cvt_pk_bf16_f32 v54, v67, v66
	s_nop 1
	v_cndmask_b32_e32 v58, 0, v230, vcc
	v_add_f32_e32 v44, v44, v58
	v_cndmask_b32_e32 v58, 0, v231, vcc
	v_cmp_gt_f32_e32 vcc, s30, v46
	v_exp_f32_e32 v44, v44
	s_nop 0
	v_cndmask_b32_e32 v59, 0, v230, vcc
	v_add_f32_e32 v46, v46, v59
	v_exp_f32_e32 v46, v46
	v_cndmask_b32_e32 v60, 0, v231, vcc
	v_ldexp_f32 v44, v44, v58
	v_pk_add_f32 v[58:59], v[66:67], v[44:45]
	v_ldexp_f32 v61, v46, v60
	v_sub_f32_e32 v46, v62, v195
	v_cmp_gt_f32_e32 vcc, s30, v46
	s_nop 1
	v_cndmask_b32_e32 v60, 0, v230, vcc
	v_add_f32_e32 v46, v46, v60
	v_exp_f32_e32 v62, v46
	v_sub_f32_e32 v46, v47, v195
	v_cmp_gt_f32_e64 s[12:13], s30, v46
	s_nop 1
	v_cndmask_b32_e64 v47, 0, v230, s[12:13]
	v_add_f32_e32 v46, v46, v47
	v_cndmask_b32_e64 v47, 0, v231, s[12:13]
	v_cmp_gt_f32_e64 s[12:13], s30, v71
	v_exp_f32_e32 v46, v46
	s_nop 0
	v_cndmask_b32_e64 v60, 0, v230, s[12:13]
	v_add_f32_e32 v60, v71, v60
	v_exp_f32_e32 v71, v60
	v_ldexp_f32 v60, v46, v47
	v_sub_f32_e32 v47, v63, v195
	v_cndmask_b32_e64 v46, 0, v231, s[12:13]
	v_and_b32_e32 v63, 0xffff, v168
	v_ldexp_f32 v46, v71, v46
	v_lshl_or_b32 v63, v172, 16, v63
	v_add_u32_e32 v71, v181, v224
	ds_write2_b32 v71, v63, v72 offset1:36
	v_and_b32_e32 v63, 0xffff, v169
	v_lshrrev_b32_e32 v72, 16, v169
	v_lshl_or_b32 v63, v173, 16, v63
	v_and_or_b32 v72, v173, s31, v72
	ds_write2_b32 v71, v63, v72 offset0:72 offset1:108
	v_and_b32_e32 v63, 0xffff, v170
	v_lshrrev_b32_e32 v72, 16, v170
	v_lshl_or_b32 v63, v174, 16, v63
	v_and_or_b32 v72, v174, s31, v72
	ds_write2_b32 v71, v63, v72 offset0:144 offset1:180
	v_and_b32_e32 v63, 0xffff, v171
	v_lshrrev_b32_e32 v72, 16, v171
	v_lshl_or_b32 v63, v175, 16, v63
	v_and_or_b32 v72, v175, s31, v72
	ds_write2_b32 v71, v63, v72 offset0:216 offset1:252
	v_and_b32_e32 v63, 0xffff, v160
	v_lshrrev_b32_e32 v72, 16, v160
	s_waitcnt vmcnt(2)
	v_lshl_or_b32 v63, v164, 16, v63
	v_add_u32_e32 v71, v181, v225
	v_and_or_b32 v72, v164, s31, v72
	ds_write2_b32 v71, v63, v72 offset1:36
	v_and_b32_e32 v63, 0xffff, v161
	v_lshrrev_b32_e32 v72, 16, v161
	v_lshl_or_b32 v63, v165, 16, v63
	v_and_or_b32 v72, v165, s31, v72
	ds_write2_b32 v71, v63, v72 offset0:72 offset1:108
	v_and_b32_e32 v63, 0xffff, v162
	v_lshrrev_b32_e32 v72, 16, v162
	v_lshl_or_b32 v63, v166, 16, v63
	v_and_or_b32 v72, v166, s31, v72
	ds_write2_b32 v71, v63, v72 offset0:144 offset1:180
	v_and_b32_e32 v63, 0xffff, v163
	v_lshrrev_b32_e32 v72, 16, v163
	v_lshl_or_b32 v63, v167, 16, v63
	v_and_or_b32 v72, v167, s31, v72
	ds_write2_b32 v71, v63, v72 offset0:216 offset1:252
	s_waitcnt vmcnt(3)
	v_and_b32_e32 v63, 0xffff, v152
	v_lshrrev_b32_e32 v72, 16, v152
	s_waitcnt vmcnt(1)
	v_lshl_or_b32 v63, v156, 16, v63
	v_and_or_b32 v72, v156, s31, v72
	v_add_u32_e32 v73, 0x800, v71
	ds_write2_b32 v73, v63, v72 offset0:64 offset1:100
	v_and_b32_e32 v63, 0xffff, v153
	v_lshrrev_b32_e32 v72, 16, v153
	v_lshl_or_b32 v63, v157, 16, v63
	v_and_or_b32 v72, v157, s31, v72
	ds_write2_b32 v73, v63, v72 offset0:136 offset1:172
	v_and_b32_e32 v63, 0xffff, v154
	v_lshrrev_b32_e32 v72, 16, v154
	v_lshl_or_b32 v63, v158, 16, v63
	v_and_or_b32 v72, v158, s31, v72
	ds_write2_b32 v73, v63, v72 offset0:208 offset1:244
	v_and_b32_e32 v63, 0xffff, v155
	v_lshrrev_b32_e32 v72, 16, v155
	v_lshl_or_b32 v63, v159, 16, v63
	v_and_or_b32 v72, v159, s31, v72
	v_add_u32_e32 v73, 0xc00, v71
	ds_write2_b32 v73, v63, v72 offset0:24 offset1:60
	v_and_b32_e32 v63, 0xffff, v144
	v_lshrrev_b32_e32 v72, 16, v144
	s_waitcnt vmcnt(0)
	v_lshl_or_b32 v63, v148, 16, v63
	v_and_or_b32 v72, v148, s31, v72
	v_add_u32_e32 v73, 0x1000, v71
	ds_write2_b32 v73, v63, v72 offset0:128 offset1:164
	v_and_b32_e32 v63, 0xffff, v145
	v_lshrrev_b32_e32 v72, 16, v145
	v_lshl_or_b32 v63, v149, 16, v63
	v_and_or_b32 v72, v149, s31, v72
	ds_write2_b32 v73, v63, v72 offset0:200 offset1:236
	v_and_b32_e32 v63, 0xffff, v146
	v_lshrrev_b32_e32 v72, 16, v146
	v_lshl_or_b32 v63, v150, 16, v63
	v_and_or_b32 v72, v150, s31, v72
	v_add_u32_e32 v71, 0x1400, v71
	ds_write2_b32 v71, v63, v72 offset0:16 offset1:52
	v_and_b32_e32 v63, 0xffff, v147
	v_lshrrev_b32_e32 v72, 16, v147
	v_lshl_or_b32 v63, v151, 16, v63
	v_and_or_b32 v72, v151, s31, v72
	ds_write2_b32 v71, v63, v72 offset0:88 offset1:124
	s_waitcnt lgkmcnt(0)
	ds_read_b128 v[72:75], v93
	ds_read_b128 v[80:83], v93 offset:32
	ds_read_b128 v[84:87], v93 offset:4608
	v_pk_mul_f32 v[30:31], v[30:31], v[46:47] op_sel_hi:[1,0]
	v_pk_mul_f32 v[28:29], v[28:29], v[46:47] op_sel_hi:[1,0]
	v_pk_mul_f32 v[26:27], v[26:27], v[46:47] op_sel_hi:[1,0]
	v_pk_mul_f32 v[24:25], v[24:25], v[46:47] op_sel_hi:[1,0]
	v_pk_mul_f32 v[22:23], v[22:23], v[46:47] op_sel_hi:[1,0]
	v_pk_mul_f32 v[20:21], v[20:21], v[46:47] op_sel_hi:[1,0]
	v_pk_mul_f32 v[18:19], v[18:19], v[46:47] op_sel_hi:[1,0]
	v_pk_mul_f32 v[16:17], v[16:17], v[46:47] op_sel_hi:[1,0]
	v_pk_mul_f32 v[14:15], v[14:15], v[46:47] op_sel_hi:[1,0]
	v_pk_mul_f32 v[12:13], v[12:13], v[46:47] op_sel_hi:[1,0]
	s_waitcnt lgkmcnt(2)
	v_mfma_f32_32x32x16_bf16 v[16:31], v[72:75], v[76:79], v[16:31]
	v_mul_f32_e64 v10, v10, v46
	v_mul_f32_e64 v11, v11, v46
	v_mul_f32_e64 v8, v8, v46
	v_mul_f32_e64 v9, v9, v46
	v_mul_f32_e64 v6, v6, v46
	v_mul_f32_e64 v7, v7, v46
	v_pk_mul_f32 v[4:5], v[4:5], v[46:47] op_sel_hi:[1,0]
	v_pk_mul_f32 v[2:3], v[2:3], v[46:47] op_sel_hi:[1,0]
	v_pk_mul_f32 v[0:1], v[0:1], v[46:47] op_sel_hi:[1,0]
	ds_read_b128 v[72:75], v93 offset:4640
	v_cmp_gt_f32_e64 s[12:13], s30, v47
	s_waitcnt lgkmcnt(1)
	v_mfma_f32_32x32x16_bf16 v[0:15], v[84:87], v[76:79], v[0:15]
	v_cvt_pk_bf16_f32 v55, v61, v60
	v_cndmask_b32_e64 v48, 0, v230, s[12:13]
	v_add_f32_e32 v47, v47, v48
	v_exp_f32_e32 v47, v47
	v_cndmask_b32_e32 v48, 0, v231, vcc
	v_ldexp_f32 v49, v62, v48
	v_cndmask_b32_e64 v48, 0, v231, s[12:13]
	v_ldexp_f32 v48, v47, v48
	v_pk_add_f32 v[76:77], v[60:61], v[48:49]
	ds_read_b128 v[60:63], v93 offset:64
	v_mfma_f32_32x32x16_bf16 v[16:31], v[80:83], v[52:55], v[16:31]
	v_add_f32_e32 v47, v68, v70
	s_waitcnt lgkmcnt(1)
	v_mfma_f32_32x32x16_bf16 v[0:15], v[72:75], v[52:55], v[0:15]
	v_cvt_pk_bf16_f32 v54, v35, v34
	v_add_f32_e32 v34, v47, v69
	v_add_f32_e32 v34, v90, v34
	v_cvt_pk_bf16_f32 v52, v70, v88
	ds_read_b128 v[64:67], v93 offset:4672
	ds_read_b128 v[70:73], v93 offset:96
	v_add_f32_e32 v34, v92, v34
	v_add_f32_e32 v33, v33, v34
	v_add_f32_e32 v32, v32, v33
	v_add_f32_e32 v37, v37, v32
	ds_read_b128 v[32:35], v93 offset:4704
	v_cvt_pk_bf16_f32 v53, v89, v91
	v_cvt_pk_bf16_f32 v55, v39, v38
	v_add_f32_e32 v36, v36, v37
	s_waitcnt lgkmcnt(3)
	v_mfma_f32_32x32x16_bf16 v[16:31], v[60:63], v[52:55], v[16:31]
	v_add_f32_e32 v36, v51, v36
	v_add_f32_e32 v47, v50, v36
	v_cvt_pk_bf16_f32 v36, v41, v40
	v_cvt_pk_bf16_f32 v37, v43, v42
	v_cvt_pk_bf16_f32 v38, v45, v44
	v_cvt_pk_bf16_f32 v39, v49, v48
	s_waitcnt lgkmcnt(0)
	s_waitcnt lgkmcnt(2)
	v_mfma_f32_32x32x16_bf16 v[0:15], v[64:67], v[52:55], v[0:15]
	s_waitcnt lgkmcnt(0)
	v_mfma_f32_32x32x16_bf16 v[0:15], v[32:35], v[36:39], v[0:15]
	v_add_f32_e32 v32, v57, v47
	v_add_f32_e32 v32, v56, v32
	v_add_f32_e32 v32, v59, v32
	v_add_f32_e32 v32, v58, v32
	v_add_f32_e32 v32, v77, v32
	v_add_f32_e32 v144, v76, v32
	v_fmac_f32_e32 v144, v233, v46
	v_mfma_f32_32x32x16_bf16 v[16:31], v[70:73], v[36:39], v[16:31]
	s_cbranch_scc1 .LBB0_812
	v_mov_b64_e32 v[178:179], v[114:115]
	v_mov_b64_e32 v[32:33], v[116:117]
	v_mov_b64_e32 v[36:37], v[124:125]
	v_mov_b64_e32 v[40:41], v[120:121]
	v_mov_b64_e32 v[44:45], v[128:129]
	v_mov_b64_e32 v[48:49], v[132:133]
	v_mov_b64_e32 v[56:57], v[140:141]
	v_mov_b64_e32 v[52:53], v[136:137]
	v_mov_b64_e32 v[176:177], v[112:113]
	v_mov_b64_e32 v[34:35], v[118:119]
	v_mov_b64_e32 v[38:39], v[126:127]
	v_mov_b64_e32 v[42:43], v[122:123]
	v_mov_b64_e32 v[46:47], v[130:131]
	v_mov_b64_e32 v[50:51], v[134:135]
	v_mov_b64_e32 v[58:59], v[142:143]
	v_mov_b64_e32 v[54:55], v[138:139]
	v_mov_b32_e32 v234, v195
	v_mov_b32_e32 v233, v144
	s_branch .LBB0_804
